# P0: 15 RMSNorm row loads per wave issued before the weight-transpose loop (the x stream overlaps the transposes); on top of v60
# speedup vs baseline: 1.0217x; 1.0122x over previous
.LBB0_48:
	v_writelane_b32 v252, s24, 48
	s_load_dwordx16 s[40:55], s[0:1], 0x0
	s_load_dword s2, s[0:1], 0xf8
	v_writelane_b32 v252, s25, 49
	v_writelane_b32 v252, s26, 50
	v_writelane_b32 v252, s27, 51
	v_writelane_b32 v252, s28, 52
	v_writelane_b32 v252, s29, 53
	v_writelane_b32 v252, s30, 54
	v_writelane_b32 v252, s31, 55
	s_waitcnt lgkmcnt(0)
	s_lshl_b32 s38, s2, 3
	s_lshl_b32 s2, s83, 3
	v_readlane_b32 s3, v252, 47
	s_add_i32 s62, s2, s3
	s_cmpk_gt_i32 s62, 0x87f
	s_cbranch_scc1 .LBB0_59
	v_readlane_b32 s2, v252, 47
	s_lshl_b32 s2, s2, 14
	v_lshrrev_b32_e32 v1, 5, v228
	v_and_b32_e32 v2, 31, v0
	s_load_dwordx8 s[16:23], s[0:1], 0xc0
	s_add_i32 s4, s2, 0
	v_lshlrev_b32_e32 v2, 2, v2
	v_mul_u32_u24_e32 v6, 0x84, v1
	v_add3_u32 v16, s4, v2, v6
	v_lshlrev_b32_e32 v6, 3, v0
	v_lshrrev_b32_e32 v17, 3, v228
	v_and_b32_e32 v6, 56, v6
	v_mov_b32_e32 v3, 0
	v_mul_u32_u24_e32 v8, 0x84, v6
	v_lshlrev_b32_e32 v9, 2, v17
	s_waitcnt lgkmcnt(0)
	v_lshl_add_u64 v[4:5], s[18:19], 0, v[2:3]
	v_add3_u32 v18, s4, v8, v9
	v_lshl_add_u64 v[8:9], s[22:23], 0, v[2:3]
	s_load_dwordx16 s[16:31], s[0:1], 0x40
	v_lshlrev_b32_e32 v6, 1, v6
	v_mov_b32_e32 v7, v3
	v_lshl_add_u64 v[14:15], s[12:13], 0, v[6:7]
	s_mov_b64 s[2:3], 0xa00000
	v_lshl_add_u64 v[6:7], v[14:15], 0, s[2:3]
	s_mov_b64 s[2:3], 0x800000
	v_lshl_add_u64 v[10:11], v[14:15], 0, s[2:3]
	s_mov_b64 s[2:3], 0x200000
	s_lshl_b32 s4, s62, 1
	s_mov_b32 s7, 0
	v_or_b32_e32 v19, 8, v17
	v_or_b32_e32 v20, 16, v17
	v_or_b32_e32 v21, 24, v17
	s_waitcnt lgkmcnt(0)
	v_lshl_add_u64 v[12:13], s[16:17], 0, v[2:3]
	v_lshl_add_u64 v[14:15], v[14:15], 0, s[2:3]
	s_lshl_b32 s2, s62, 5
	s_lshl_b32 s3, s38, 5
	s_lshl_b32 s10, s62, 7
	s_lshl_b32 s11, s38, 7
	s_lshl_b32 s14, s62, 2
	s_lshl_b32 s15, s38, 2
	s_add_i32 s16, s4, 0x1f400
	s_lshl_b32 s17, s38, 1
	s_movk_i32 s18, 0x3000
	s_movk_i32 s19, 0x7fff
	s_mov_b32 s20, 0xffff0000
	v_add_u32_e32 v22, 0x400, v16
	v_add_u32_e32 v23, 0x800, v16
	v_add_u32_e32 v24, 0xc00, v16
	v_add_u32_e32 v25, 0x1000, v16
	v_add_u32_e32 v26, 0x1400, v16
	v_add_u32_e32 v27, 0x1800, v16
	v_add_u32_e32 v28, 0x1c00, v16
	s_mov_b32 s21, s62
	s_ashr_i32 s99, s62, 31
	s_mov_b32 s98, s62
	s_lshl_b64 s[98:99], s[98:99], 12
	s_add_u32 s98, s40, s98
	s_addc_u32 s99, s41, s99
	v_lshlrev_b32_e32 v130, 4, v228
	s_add_u32 s98, s98, 0x800000
	s_addc_u32 s99, s99, 0
	global_load_dwordx4 v[106:109], v130, s[98:99] nt
	global_load_dwordx4 v[94:97], v130, s[98:99] offset:1024 nt
	global_load_dwordx4 v[86:89], v130, s[98:99] offset:2048 nt
	global_load_dwordx4 v[90:93], v130, s[98:99] offset:3072 nt
	s_add_u32 s98, s98, 0x800000
	s_addc_u32 s99, s99, 0
	global_load_dwordx4 v[126:129], v130, s[98:99] nt
	global_load_dwordx4 v[122:125], v130, s[98:99] offset:1024 nt
	global_load_dwordx4 v[118:121], v130, s[98:99] offset:2048 nt
	global_load_dwordx4 v[114:117], v130, s[98:99] offset:3072 nt
	s_add_u32 s98, s98, 0x800000
	s_addc_u32 s99, s99, 0
	global_load_dwordx4 v[110:113], v130, s[98:99] nt
	global_load_dwordx4 v[102:105], v130, s[98:99] offset:1024 nt
	global_load_dwordx4 v[98:101], v130, s[98:99] offset:2048 nt
	global_load_dwordx4 v[82:85], v130, s[98:99] offset:3072 nt
	s_add_u32 s98, s98, 0x800000
	s_addc_u32 s99, s99, 0
	global_load_dwordx4 v[78:81], v130, s[98:99] nt
	global_load_dwordx4 v[74:77], v130, s[98:99] offset:1024 nt
	global_load_dwordx4 v[70:73], v130, s[98:99] offset:2048 nt
	s_branch .LBB0_51

.LBB0_66:
	s_andn2_b64 vcc, exec, s[4:5]
	s_cbranch_vccnz .LBB0_69
	s_ashr_i32 s63, s62, 31
	s_lshl_b64 s[2:3], s[62:63], 12
	s_add_u32 s4, s40, s2
	s_addc_u32 s5, s41, s3
	v_lshlrev_b32_e32 v130, 4, v228
	global_load_dwordx4 v[26:29], v130, s[4:5] nt
	global_load_dwordx4 v[22:25], v130, s[4:5] offset:1024 nt
	global_load_dwordx4 v[18:21], v130, s[4:5] offset:2048 nt
	global_load_dwordx4 v[10:13], v130, s[4:5] offset:3072 nt
	v_mov_b32_e32 v131, 0
	s_mov_b32 s2, 0x800000
	v_lshl_add_u64 v[30:31], s[4:5], 0, v[130:131]
	v_add_co_u32_e32 v2, vcc, s2, v30
	s_mov_b64 s[18:19], 0x800000
	s_nop 0
	v_addc_co_u32_e32 v3, vcc, 0, v31, vcc
	v_lshl_add_u64 v[2:3], v[30:31], 0, s[18:19]
	s_mov_b32 s22, 0x1000000
	global_load_dwordx4 v[2:5], v130, s[54:55]
	v_add_co_u32_e32 v46, vcc, s22, v30
	s_mov_b32 s21, 0x1800000
	s_nop 0
	v_addc_co_u32_e32 v47, vcc, 0, v31, vcc
	v_add_co_u32_e32 v44, vcc, s21, v30
	s_brev_b32 s3, 64
	s_nop 0
	v_addc_co_u32_e32 v45, vcc, 0, v31, vcc
	v_add_co_u32_e32 v42, vcc, s3, v30
	s_mov_b32 s20, 0x2800000
	s_nop 0
	v_addc_co_u32_e32 v43, vcc, 0, v31, vcc
	s_mov_b64 s[16:17], 0x2800000
	v_add_co_u32_e32 v38, vcc, s20, v30
	s_mov_b32 s20, 0x358637bd
	v_lshl_add_u64 v[32:33], v[30:31], 0, s[16:17]
	s_mov_b32 s16, 0x3a800000
	v_mov_b64_e32 v[134:135], s[20:21]
	v_addc_co_u32_e32 v39, vcc, 0, v31, vcc
	s_mov_b32 s20, 0x3000000
	s_mov_b32 s23, 0x3800000
	s_mov_b64 s[14:15], 0x1000000
	s_mov_b64 s[12:13], 0x1800000
	s_mov_b64 s[8:9], 0x2000000
	s_mov_b64 s[24:25], 0x3000000
	v_lshl_add_u64 v[40:41], v[30:31], 0, s[14:15]
	v_lshl_add_u64 v[36:37], v[30:31], 0, s[12:13]
	v_lshl_add_u64 v[34:35], v[30:31], 0, s[8:9]
	s_mov_b64 s[26:27], 0x3800000
	v_lshl_add_u64 v[132:133], v[30:31], 0, s[26:27]
	s_lshl_b64 s[10:11], s[62:63], 11
	s_add_u32 s4, s6, s10
	s_addc_u32 s5, s7, s11
	s_cmpk_gt_i32 s62, 0x1ff
	global_load_dwordx4 v[66:69], v[34:35], off offset:3072 nt
	global_load_dwordx4 v[58:61], v[32:33], off offset:1024 nt
	global_load_dwordx4 v[54:57], v[32:33], off offset:2048 nt
	global_load_dwordx4 v[62:65], v[38:39], off nt
	global_load_dwordx4 v[50:53], v[32:33], off offset:3072 nt
	s_waitcnt vmcnt(9)
	v_mul_f32_e32 v1, v27, v27
	v_mul_f32_e32 v6, v29, v29
	s_waitcnt vmcnt(8)
	v_mul_f32_e32 v7, v23, v23
	v_mul_f32_e32 v8, v25, v25
	s_waitcnt vmcnt(7)
	v_mul_f32_e32 v9, v19, v19
	v_mul_f32_e32 v14, v21, v21
	v_fmac_f32_e32 v1, v26, v26
	v_fmac_f32_e32 v6, v28, v28
	v_fmac_f32_e32 v7, v22, v22
	v_fmac_f32_e32 v8, v24, v24
	s_waitcnt vmcnt(6)
	v_mul_f32_e32 v15, v11, v11
	v_mul_f32_e32 v16, v13, v13
	v_fmac_f32_e32 v9, v18, v18
	v_fmac_f32_e32 v14, v20, v20
	v_add_f32_e32 v1, v1, v6
	v_add_f32_e32 v6, v7, v8
	v_fmac_f32_e32 v15, v10, v10
	v_fmac_f32_e32 v16, v12, v12
	v_add_f32_e32 v7, v9, v14
	v_add_f32_e32 v1, v1, v6
	v_add_f32_e32 v8, v15, v16
	v_add_f32_e32 v1, v1, v7
	v_add_f32_e32 v1, v1, v8
	s_waitcnt vmcnt(6)
	v_mul_f32_e32 v9, v107, v107
	v_mul_f32_e32 v14, v109, v109
	v_add_f32_dpp v1, v1, v1 quad_perm:[1,0,3,2] row_mask:0xf bank_mask:0xf bound_ctrl:1
	s_waitcnt vmcnt(6)
	v_mul_f32_e32 v16, v95, v95
	v_fmac_f32_e32 v9, v106, v106
	v_add_f32_dpp v1, v1, v1 quad_perm:[2,3,0,1] row_mask:0xf bank_mask:0xf bound_ctrl:1
	v_fmac_f32_e32 v14, v108, v108
	v_fmac_f32_e32 v16, v94, v94
	v_add_f32_dpp v1, v1, v1 row_half_mirror row_mask:0xf bank_mask:0xf bound_ctrl:1
	v_add_f32_e32 v6, v9, v14
	s_nop 0
	v_add_f32_dpp v1, v1, v1 row_ror:8 row_mask:0xf bank_mask:0xf bound_ctrl:1
	v_mov_b32_e32 v7, v1
	s_nop 1
	v_permlane16_swap_b32_e32 v1, v7
	v_add_f32_e32 v15, v1, v7
	v_mul_f32_e32 v1, v97, v97
	v_fmac_f32_e32 v1, v96, v96
	v_add_f32_e32 v1, v16, v1
	v_add_f32_e32 v1, v6, v1
	s_waitcnt vmcnt(6)
	v_mul_f32_e32 v6, v87, v87
	v_mul_f32_e32 v7, v89, v89
	v_fmac_f32_e32 v6, v86, v86
	v_fmac_f32_e32 v7, v88, v88
	v_add_f32_e32 v6, v6, v7
	v_add_f32_e32 v1, v1, v6
	s_waitcnt vmcnt(6)
	v_mul_f32_e32 v6, v91, v91
	v_mul_f32_e32 v7, v93, v93
	v_fmac_f32_e32 v6, v90, v90
	v_fmac_f32_e32 v7, v92, v92
	v_add_f32_e32 v6, v6, v7
	v_add_f32_e32 v1, v1, v6
	v_mov_b32_e32 v17, v15
	s_nop 1
	v_permlane32_swap_b32_e32 v15, v17
	v_add_f32_dpp v1, v1, v1 quad_perm:[1,0,3,2] row_mask:0xf bank_mask:0xf bound_ctrl:1
	s_nop 1
	v_add_f32_dpp v1, v1, v1 quad_perm:[2,3,0,1] row_mask:0xf bank_mask:0xf bound_ctrl:1
	s_nop 1
	v_add_f32_dpp v1, v1, v1 row_half_mirror row_mask:0xf bank_mask:0xf bound_ctrl:1
	s_nop 1
	v_add_f32_dpp v1, v1, v1 row_ror:8 row_mask:0xf bank_mask:0xf bound_ctrl:1
	v_mov_b32_e32 v6, v1
	s_nop 1
	v_permlane16_swap_b32_e32 v1, v6
	v_add_f32_e32 v14, v1, v6
	v_mov_b32_e32 v16, v14
	s_nop 1
	v_permlane32_swap_b32_e32 v14, v16
	v_pk_add_f32 v[14:15], v[14:15], v[16:17]
	global_load_dwordx4 v[6:9], v130, s[54:55] offset:1024
	v_pk_fma_f32 v[136:137], v[14:15], s[16:17], v[134:135] op_sel_hi:[1,0,0]
	s_movk_i32 s17, 0x7fff
	v_mul_f32_e32 v1, 0x4b800000, v137
	v_cmp_gt_f32_e32 vcc, s2, v137
	s_nop 1
	v_cndmask_b32_e32 v1, v137, v1, vcc
	v_rsq_f32_e32 v1, v1
	s_nop 0
	v_mul_f32_e32 v14, 0x45800000, v1
	v_cndmask_b32_e32 v48, v1, v14, vcc
	global_load_dwordx4 v[14:17], v130, s[54:55] offset:2048
	v_pk_mul_f32 v[146:147], v[10:11], v[48:49] op_sel_hi:[1,0]
	v_pk_mul_f32 v[148:149], v[12:13], v[48:49] op_sel_hi:[1,0]
	global_load_dwordx4 v[10:13], v130, s[54:55] offset:3072
	v_pk_mul_f32 v[26:27], v[26:27], v[48:49] op_sel_hi:[1,0]
	v_pk_mul_f32 v[144:145], v[20:21], v[48:49] op_sel_hi:[1,0]
	s_waitcnt vmcnt(3)
	v_pk_mul_f32 v[20:21], v[2:3], v[26:27]
	v_pk_mul_f32 v[28:29], v[28:29], v[48:49] op_sel_hi:[1,0]
	v_bfe_u32 v1, v20, 16, 1
	v_pk_mul_f32 v[142:143], v[18:19], v[48:49] op_sel_hi:[1,0]
	v_pk_mul_f32 v[18:19], v[4:5], v[28:29]
	v_add3_u32 v1, v20, v1, s17
	v_bfe_u32 v20, v21, 16, 1
	v_add3_u32 v20, v21, v20, s17
	v_bfe_u32 v21, v18, 16, 1
	v_add3_u32 v21, v18, v21, s17
	v_bfe_u32 v18, v19, 16, 1
	v_pk_mul_f32 v[138:139], v[22:23], v[48:49] op_sel_hi:[1,0]
	v_add3_u32 v22, v19, v18, s17
	v_add_co_u32_e32 v18, vcc, s20, v30
	v_lshrrev_b32_e32 v1, 16, v1
	s_nop 0
	v_addc_co_u32_e32 v19, vcc, 0, v31, vcc
	s_mov_b32 s20, 0xffff0000
	v_and_or_b32 v150, v20, s20, v1
	v_lshrrev_b32_e32 v1, 16, v21
	v_add_co_u32_e32 v20, vcc, s23, v30
	v_and_or_b32 v151, v22, s20, v1
	s_nop 0
	v_addc_co_u32_e32 v21, vcc, 0, v31, vcc
	v_lshl_add_u64 v[22:23], v[30:31], 0, s[24:25]
	v_pk_mul_f32 v[140:141], v[24:25], v[48:49] op_sel_hi:[1,0]
	global_load_dwordx4 v[42:45], v[22:23], off offset:1024 nt
	s_nop 0
	global_load_dwordx4 v[38:41], v[22:23], off offset:2048 nt
	global_load_dwordx4 v[46:49], v[18:19], off nt
	global_load_dwordx4 v[34:37], v[22:23], off offset:3072 nt
	global_load_dwordx4 v[26:29], v[132:133], off offset:1024 nt
	s_nop 0
	global_load_dwordx4 v[22:25], v[132:133], off offset:2048 nt
	global_load_dwordx4 v[30:33], v[20:21], off nt
	s_nop 0
	global_load_dwordx4 v[18:21], v[132:133], off offset:3072 nt
	v_lshlrev_b32_e32 v132, 3, v228
	global_store_dwordx2 v132, v[150:151], s[4:5] sc1
	v_cmp_gt_f32_e32 vcc, s2, v136
	s_mov_b32 s23, 0x400000
	s_waitcnt vmcnt(11)
	v_pk_mul_f32 v[138:139], v[6:7], v[138:139]
	s_nop 0
	v_bfe_u32 v1, v138, 16, 1
	v_bfe_u32 v133, v139, 16, 1
	v_add3_u32 v1, v138, v1, s17
	v_add3_u32 v133, v139, v133, s17
	v_pk_mul_f32 v[138:139], v[8:9], v[140:141]
	v_lshrrev_b32_e32 v1, 16, v1
	v_bfe_u32 v137, v138, 16, 1
	v_add3_u32 v137, v138, v137, s17
	v_bfe_u32 v138, v139, 16, 1
	v_add3_u32 v139, v139, v138, s17
	v_and_or_b32 v138, v133, s20, v1
	v_lshrrev_b32_e32 v1, 16, v137
	v_and_or_b32 v139, v139, s20, v1
	global_store_dwordx2 v132, v[138:139], s[4:5] offset:512 sc1
	s_waitcnt vmcnt(11)
	v_pk_mul_f32 v[138:139], v[14:15], v[142:143]
	s_nop 0
	v_bfe_u32 v1, v138, 16, 1
	v_bfe_u32 v133, v139, 16, 1
	v_add3_u32 v1, v138, v1, s17
	v_add3_u32 v133, v139, v133, s17
	v_pk_mul_f32 v[138:139], v[16:17], v[144:145]
	v_lshrrev_b32_e32 v1, 16, v1
	v_bfe_u32 v137, v138, 16, 1
	v_add3_u32 v137, v138, v137, s17
	v_bfe_u32 v138, v139, 16, 1
	v_add3_u32 v139, v139, v138, s17
	v_and_or_b32 v138, v133, s20, v1
	v_lshrrev_b32_e32 v1, 16, v137
	v_and_or_b32 v139, v139, s20, v1
	global_store_dwordx2 v132, v[138:139], s[4:5] offset:1024 sc1
	s_waitcnt vmcnt(11)
	v_pk_mul_f32 v[138:139], v[10:11], v[146:147]
	s_nop 0
	v_bfe_u32 v1, v138, 16, 1
	v_bfe_u32 v133, v139, 16, 1
	v_add3_u32 v1, v138, v1, s17
	v_add3_u32 v133, v139, v133, s17
	v_pk_mul_f32 v[138:139], v[12:13], v[148:149]
	v_lshrrev_b32_e32 v1, 16, v1
	v_bfe_u32 v137, v138, 16, 1
	v_add3_u32 v137, v138, v137, s17
	v_bfe_u32 v138, v139, 16, 1
	v_add3_u32 v139, v139, v138, s17
	v_and_or_b32 v138, v133, s20, v1
	v_mul_f32_e32 v1, 0x4b800000, v136
	v_cndmask_b32_e32 v1, v136, v1, vcc
	v_rsq_f32_e32 v1, v1
	v_lshrrev_b32_e32 v133, 16, v137
	v_and_or_b32 v139, v139, s20, v133
	global_store_dwordx2 v132, v[138:139], s[4:5] offset:1536 sc1
	v_mul_f32_e32 v133, 0x45800000, v1
	v_cndmask_b32_e32 v136, v1, v133, vcc
	v_pk_mul_f32 v[106:107], v[106:107], v[136:137] op_sel_hi:[1,0]
	v_pk_mul_f32 v[108:109], v[108:109], v[136:137] op_sel_hi:[1,0]
	v_pk_mul_f32 v[106:107], v[2:3], v[106:107]
	v_pk_mul_f32 v[94:95], v[94:95], v[136:137] op_sel_hi:[1,0]
	v_bfe_u32 v1, v106, 16, 1
	v_add3_u32 v1, v106, v1, s17
	v_bfe_u32 v106, v107, 16, 1
	v_add3_u32 v133, v107, v106, s17
	v_pk_mul_f32 v[106:107], v[4:5], v[108:109]
	v_lshrrev_b32_e32 v1, 16, v1
	v_bfe_u32 v108, v106, 16, 1
	v_add3_u32 v106, v106, v108, s17
	v_bfe_u32 v108, v107, 16, 1
	v_add3_u32 v107, v107, v108, s17
	v_and_or_b32 v108, v133, s20, v1
	v_lshrrev_b32_e32 v1, 16, v106
	v_mov_b32_e32 v133, v131
	v_and_or_b32 v109, v107, s20, v1
	v_lshl_add_u64 v[106:107], s[4:5], 0, v[132:133]
	v_pk_mul_f32 v[94:95], v[6:7], v[94:95]
	v_add_co_u32_e32 v138, vcc, s23, v106
	v_bfe_u32 v1, v94, 16, 1
	s_nop 0
	v_addc_co_u32_e32 v139, vcc, 0, v107, vcc
	v_pk_mul_f32 v[96:97], v[96:97], v[136:137] op_sel_hi:[1,0]
	v_add3_u32 v1, v94, v1, s17
	v_bfe_u32 v94, v95, 16, 1
	global_store_dwordx2 v[138:139], v[108:109], off sc1
	v_add3_u32 v108, v95, v94, s17
	v_pk_mul_f32 v[94:95], v[8:9], v[96:97]
	v_pk_mul_f32 v[86:87], v[86:87], v[136:137] op_sel_hi:[1,0]
	v_bfe_u32 v96, v94, 16, 1
	v_add3_u32 v96, v94, v96, s17
	v_bfe_u32 v94, v95, 16, 1
	v_lshrrev_b32_e32 v1, 16, v1
	v_add3_u32 v95, v95, v94, s17
	v_and_or_b32 v94, v108, s20, v1
	v_lshrrev_b32_e32 v1, 16, v96
	v_pk_mul_f32 v[86:87], v[14:15], v[86:87]
	v_and_or_b32 v95, v95, s20, v1
	s_mov_b64 s[4:5], 0x400000
	v_bfe_u32 v1, v86, 16, 1
	v_pk_mul_f32 v[88:89], v[88:89], v[136:137] op_sel_hi:[1,0]
	v_lshl_add_u64 v[96:97], v[106:107], 0, s[4:5]
	v_add3_u32 v1, v86, v1, s17
	v_bfe_u32 v86, v87, 16, 1
	global_store_dwordx2 v[96:97], v[94:95], off offset:512 sc1
	v_add3_u32 v94, v87, v86, s17
	v_pk_mul_f32 v[86:87], v[16:17], v[88:89]
	v_lshrrev_b32_e32 v1, 16, v1
	v_bfe_u32 v88, v86, 16, 1
	v_add3_u32 v88, v86, v88, s17
	v_bfe_u32 v86, v87, 16, 1
	v_add3_u32 v87, v87, v86, s17
	v_and_or_b32 v86, v94, s20, v1
	v_lshrrev_b32_e32 v1, 16, v88
	v_pk_mul_f32 v[90:91], v[90:91], v[136:137] op_sel_hi:[1,0]
	v_and_or_b32 v87, v87, s20, v1
	global_store_dwordx2 v[96:97], v[86:87], off offset:1024 sc1
	v_pk_mul_f32 v[86:87], v[10:11], v[90:91]
	v_pk_mul_f32 v[92:93], v[92:93], v[136:137] op_sel_hi:[1,0]
	v_bfe_u32 v1, v86, 16, 1
	v_add3_u32 v1, v86, v1, s17
	v_bfe_u32 v86, v87, 16, 1
	v_add3_u32 v88, v87, v86, s17
	v_pk_mul_f32 v[86:87], v[12:13], v[92:93]
	v_lshrrev_b32_e32 v1, 16, v1
	v_bfe_u32 v89, v86, 16, 1
	v_add3_u32 v92, v86, v89, s17
	v_bfe_u32 v86, v87, 16, 1
	v_add3_u32 v87, v87, v86, s17
	v_and_or_b32 v86, v88, s20, v1
	s_waitcnt vmcnt(23)
	v_mul_f32_e32 v1, v127, v127
	v_mul_f32_e32 v88, v129, v129
	v_fmac_f32_e32 v1, v126, v126
	v_fmac_f32_e32 v88, v128, v128
	v_add_f32_e32 v1, v1, v88
	v_mul_f32_e32 v88, v123, v123
	v_mul_f32_e32 v89, v125, v125
	v_fmac_f32_e32 v88, v122, v122
	v_fmac_f32_e32 v89, v124, v124
	v_add_f32_e32 v88, v88, v89
	v_add_f32_e32 v1, v1, v88
	v_mul_f32_e32 v88, v119, v119
	v_mul_f32_e32 v89, v121, v121
	v_fmac_f32_e32 v88, v118, v118
	v_fmac_f32_e32 v89, v120, v120
	v_add_f32_e32 v88, v88, v89
	v_add_f32_e32 v1, v1, v88
	s_waitcnt vmcnt(23)
	v_mul_f32_e32 v88, v115, v115
	v_mul_f32_e32 v89, v117, v117
	v_fmac_f32_e32 v88, v114, v114
	v_fmac_f32_e32 v89, v116, v116
	v_add_f32_e32 v88, v88, v89
	v_add_f32_e32 v1, v1, v88
	s_waitcnt vmcnt(23)
	v_mul_f32_e32 v88, v111, v111
	v_mul_f32_e32 v89, v113, v113
	v_fmac_f32_e32 v88, v110, v110
	v_fmac_f32_e32 v89, v112, v112
	v_add_f32_e32 v88, v88, v89
	v_mul_f32_e32 v89, v103, v103
	v_mul_f32_e32 v90, v105, v105
	v_fmac_f32_e32 v89, v102, v102
	v_fmac_f32_e32 v90, v104, v104
	v_add_f32_e32 v89, v89, v90
	v_add_f32_e32 v88, v88, v89
	v_mul_f32_e32 v89, v99, v99
	v_mul_f32_e32 v90, v101, v101
	v_fmac_f32_e32 v89, v98, v98
	v_fmac_f32_e32 v90, v100, v100
	v_add_f32_e32 v89, v89, v90
	v_add_f32_dpp v1, v1, v1 quad_perm:[1,0,3,2] row_mask:0xf bank_mask:0xf bound_ctrl:1
	v_add_f32_e32 v88, v88, v89
	s_waitcnt vmcnt(23)
	v_mul_f32_e32 v89, v83, v83
	v_mul_f32_e32 v90, v85, v85
	v_add_f32_dpp v1, v1, v1 quad_perm:[2,3,0,1] row_mask:0xf bank_mask:0xf bound_ctrl:1
	v_fmac_f32_e32 v89, v82, v82
	v_fmac_f32_e32 v90, v84, v84
	v_add_f32_dpp v1, v1, v1 row_half_mirror row_mask:0xf bank_mask:0xf bound_ctrl:1
	v_add_f32_e32 v89, v89, v90
	v_add_f32_e32 v88, v88, v89
	v_add_f32_dpp v1, v1, v1 row_ror:8 row_mask:0xf bank_mask:0xf bound_ctrl:1
	v_mov_b32_e32 v89, v1
	s_nop 1
	v_permlane16_swap_b32_e32 v1, v89
	v_add_f32_e32 v89, v1, v89
	s_nop 0
	v_add_f32_dpp v1, v88, v88 quad_perm:[1,0,3,2] row_mask:0xf bank_mask:0xf bound_ctrl:1
	v_mov_b32_e32 v91, v89
	s_nop 1
	v_permlane32_swap_b32_e32 v89, v91
	v_add_f32_dpp v1, v1, v1 quad_perm:[2,3,0,1] row_mask:0xf bank_mask:0xf bound_ctrl:1
	s_mov_b32 s4, 0xc00000
	s_nop 0
	v_add_f32_dpp v1, v1, v1 row_half_mirror row_mask:0xf bank_mask:0xf bound_ctrl:1
	s_nop 1
	v_add_f32_dpp v1, v1, v1 row_ror:8 row_mask:0xf bank_mask:0xf bound_ctrl:1
	v_mov_b32_e32 v88, v1
	s_nop 1
	v_permlane16_swap_b32_e32 v1, v88
	v_add_f32_e32 v88, v1, v88
	v_mov_b32_e32 v90, v88
	s_nop 1
	v_permlane32_swap_b32_e32 v88, v90
	v_pk_add_f32 v[88:89], v[88:89], v[90:91]
	s_nop 0
	v_pk_fma_f32 v[88:89], v[88:89], s[16:17], v[134:135] op_sel_hi:[1,0,0]
	s_nop 0
	v_mul_f32_e32 v1, 0x4b800000, v89
	v_cmp_gt_f32_e32 vcc, s2, v89
	s_nop 1
	v_cndmask_b32_e32 v1, v89, v1, vcc
	v_rsq_f32_e32 v1, v1
	v_lshrrev_b32_e32 v89, 16, v92
	v_and_or_b32 v87, v87, s20, v89
	global_store_dwordx2 v[96:97], v[86:87], off offset:1536 sc1
	v_mul_f32_e32 v86, 0x45800000, v1
	v_cndmask_b32_e32 v86, v1, v86, vcc
	v_pk_mul_f32 v[90:91], v[126:127], v[86:87] op_sel_hi:[1,0]
	v_pk_mul_f32 v[92:93], v[128:129], v[86:87] op_sel_hi:[1,0]
	v_pk_mul_f32 v[90:91], v[2:3], v[90:91]
	s_nop 0
	v_bfe_u32 v1, v90, 16, 1
	v_bfe_u32 v87, v91, 16, 1
	v_add3_u32 v1, v90, v1, s17
	v_add3_u32 v87, v91, v87, s17
	v_pk_mul_f32 v[90:91], v[4:5], v[92:93]
	v_lshrrev_b32_e32 v1, 16, v1
	v_bfe_u32 v89, v90, 16, 1
	v_add3_u32 v89, v90, v89, s17
	v_bfe_u32 v90, v91, 16, 1
	v_add3_u32 v91, v91, v90, s17
	v_and_or_b32 v90, v87, s20, v1
	v_lshrrev_b32_e32 v1, 16, v89
	v_add_co_u32_e32 v92, vcc, s2, v106
	v_and_or_b32 v91, v91, s20, v1
	s_nop 0
	v_addc_co_u32_e32 v93, vcc, 0, v107, vcc
	global_store_dwordx2 v[92:93], v[90:91], off sc1
	v_pk_mul_f32 v[90:91], v[122:123], v[86:87] op_sel_hi:[1,0]
	v_pk_mul_f32 v[92:93], v[124:125], v[86:87] op_sel_hi:[1,0]
	v_pk_mul_f32 v[90:91], v[6:7], v[90:91]
	v_pk_mul_f32 v[94:95], v[118:119], v[86:87] op_sel_hi:[1,0]
	v_bfe_u32 v1, v90, 16, 1
	v_bfe_u32 v89, v91, 16, 1
	v_add3_u32 v1, v90, v1, s17
	v_add3_u32 v89, v91, v89, s17
	v_pk_mul_f32 v[90:91], v[8:9], v[92:93]
	v_lshrrev_b32_e32 v1, 16, v1
	v_bfe_u32 v92, v90, 16, 1
	v_add3_u32 v92, v90, v92, s17
	v_bfe_u32 v90, v91, 16, 1
	v_add3_u32 v91, v91, v90, s17
	v_and_or_b32 v90, v89, s20, v1
	v_lshrrev_b32_e32 v1, 16, v92
	v_and_or_b32 v91, v91, s20, v1
	v_lshl_add_u64 v[92:93], v[106:107], 0, s[18:19]
	global_store_dwordx2 v[92:93], v[90:91], off offset:512 sc1
	v_pk_mul_f32 v[90:91], v[14:15], v[94:95]
	v_pk_mul_f32 v[96:97], v[120:121], v[86:87] op_sel_hi:[1,0]
	v_bfe_u32 v1, v90, 16, 1
	v_bfe_u32 v89, v91, 16, 1
	v_add3_u32 v1, v90, v1, s17
	v_add3_u32 v89, v91, v89, s17
	v_pk_mul_f32 v[90:91], v[16:17], v[96:97]
	v_lshrrev_b32_e32 v1, 16, v1
	v_bfe_u32 v94, v90, 16, 1
	v_add3_u32 v94, v90, v94, s17
	v_bfe_u32 v90, v91, 16, 1
	v_add3_u32 v91, v91, v90, s17
	v_and_or_b32 v90, v89, s20, v1
	v_lshrrev_b32_e32 v1, 16, v94
	v_pk_mul_f32 v[108:109], v[114:115], v[86:87] op_sel_hi:[1,0]
	v_and_or_b32 v91, v91, s20, v1
	v_pk_mul_f32 v[86:87], v[116:117], v[86:87] op_sel_hi:[1,0]
	global_store_dwordx2 v[92:93], v[90:91], off offset:1024 sc1
	v_pk_mul_f32 v[90:91], v[10:11], v[108:109]
	v_pk_mul_f32 v[86:87], v[12:13], v[86:87]
	v_bfe_u32 v1, v90, 16, 1
	v_add3_u32 v1, v90, v1, s17
	v_bfe_u32 v89, v91, 16, 1
	v_bfe_u32 v90, v86, 16, 1
	v_add3_u32 v89, v91, v89, s17
	v_add3_u32 v90, v86, v90, s17
	v_bfe_u32 v86, v87, 16, 1
	v_lshrrev_b32_e32 v1, 16, v1
	v_add3_u32 v87, v87, v86, s17
	v_and_or_b32 v86, v89, s20, v1
	v_mul_f32_e32 v1, 0x4b800000, v88
	v_cmp_gt_f32_e32 vcc, s2, v88
	s_nop 1
	v_cndmask_b32_e32 v1, v88, v1, vcc
	v_rsq_f32_e32 v1, v1
	v_lshrrev_b32_e32 v88, 16, v90
	v_and_or_b32 v87, v87, s20, v88
	global_store_dwordx2 v[92:93], v[86:87], off offset:1536 sc1
	v_mul_f32_e32 v86, 0x45800000, v1
	v_cndmask_b32_e32 v86, v1, v86, vcc
	v_pk_mul_f32 v[88:89], v[110:111], v[86:87] op_sel_hi:[1,0]
	v_pk_mul_f32 v[90:91], v[112:113], v[86:87] op_sel_hi:[1,0]
	v_pk_mul_f32 v[88:89], v[2:3], v[88:89]
	s_nop 0
	v_bfe_u32 v1, v88, 16, 1
	v_bfe_u32 v87, v89, 16, 1
	v_add3_u32 v1, v88, v1, s17
	v_add3_u32 v87, v89, v87, s17
	v_pk_mul_f32 v[88:89], v[4:5], v[90:91]
	v_lshrrev_b32_e32 v1, 16, v1
	v_bfe_u32 v90, v88, 16, 1
	v_add3_u32 v90, v88, v90, s17
	v_bfe_u32 v88, v89, 16, 1
	v_add3_u32 v89, v89, v88, s17
	v_and_or_b32 v88, v87, s20, v1
	v_lshrrev_b32_e32 v1, 16, v90
	v_add_co_u32_e32 v90, vcc, s4, v106
	v_and_or_b32 v89, v89, s20, v1
	s_nop 0
	v_addc_co_u32_e32 v91, vcc, 0, v107, vcc
	global_store_dwordx2 v[90:91], v[88:89], off sc1
	v_pk_mul_f32 v[88:89], v[102:103], v[86:87] op_sel_hi:[1,0]
	v_pk_mul_f32 v[90:91], v[104:105], v[86:87] op_sel_hi:[1,0]
	v_pk_mul_f32 v[92:93], v[98:99], v[86:87] op_sel_hi:[1,0]
	v_pk_mul_f32 v[94:95], v[100:101], v[86:87] op_sel_hi:[1,0]
	v_pk_mul_f32 v[82:83], v[82:83], v[86:87] op_sel_hi:[1,0]
	v_pk_mul_f32 v[84:85], v[84:85], v[86:87] op_sel_hi:[1,0]
	v_pk_mul_f32 v[86:87], v[6:7], v[88:89]
	s_mov_b64 s[4:5], 0xc00000
	v_bfe_u32 v1, v86, 16, 1
	v_add3_u32 v1, v86, v1, s17
	v_bfe_u32 v86, v87, 16, 1
	v_add3_u32 v88, v87, v86, s17
	v_pk_mul_f32 v[86:87], v[8:9], v[90:91]
	v_lshrrev_b32_e32 v1, 16, v1
	v_bfe_u32 v89, v86, 16, 1
	v_add3_u32 v89, v86, v89, s17
	v_bfe_u32 v86, v87, 16, 1
	v_add3_u32 v87, v87, v86, s17
	v_and_or_b32 v86, v88, s20, v1
	v_lshrrev_b32_e32 v1, 16, v89
	v_and_or_b32 v87, v87, s20, v1
	v_lshl_add_u64 v[88:89], v[106:107], 0, s[4:5]
	global_store_dwordx2 v[88:89], v[86:87], off offset:512 sc1
	v_pk_mul_f32 v[86:87], v[14:15], v[92:93]
	v_pk_mul_f32 v[82:83], v[10:11], v[82:83]
	v_bfe_u32 v1, v86, 16, 1
	v_add3_u32 v1, v86, v1, s17
	v_bfe_u32 v86, v87, 16, 1
	v_add3_u32 v90, v87, v86, s17
	v_pk_mul_f32 v[86:87], v[16:17], v[94:95]
	v_lshrrev_b32_e32 v1, 16, v1
	v_bfe_u32 v91, v86, 16, 1
	v_add3_u32 v91, v86, v91, s17
	v_bfe_u32 v86, v87, 16, 1
	v_add3_u32 v87, v87, v86, s17
	v_and_or_b32 v86, v90, s20, v1
	v_lshrrev_b32_e32 v1, 16, v91
	v_and_or_b32 v87, v87, s20, v1
	v_bfe_u32 v1, v82, 16, 1
	v_add3_u32 v1, v82, v1, s17
	v_bfe_u32 v82, v83, 16, 1
	global_store_dwordx2 v[88:89], v[86:87], off offset:1024 sc1
	v_add3_u32 v86, v83, v82, s17
	v_pk_mul_f32 v[82:83], v[12:13], v[84:85]
	v_lshrrev_b32_e32 v1, 16, v1
	v_bfe_u32 v84, v82, 16, 1
	v_add3_u32 v90, v82, v84, s17
	v_bfe_u32 v82, v83, 16, 1
	v_add3_u32 v83, v83, v82, s17
	v_and_or_b32 v82, v86, s20, v1
	s_waitcnt vmcnt(28)
	v_mul_f32_e32 v1, v79, v79
	v_mul_f32_e32 v84, v81, v81
	v_fmac_f32_e32 v1, v78, v78
	v_fmac_f32_e32 v84, v80, v80
	v_add_f32_e32 v1, v1, v84
	v_mul_f32_e32 v84, v75, v75
	v_mul_f32_e32 v85, v77, v77
	v_fmac_f32_e32 v84, v74, v74
	v_fmac_f32_e32 v85, v76, v76
	v_add_f32_e32 v84, v84, v85
	v_add_f32_e32 v1, v1, v84
	v_mul_f32_e32 v84, v71, v71
	v_mul_f32_e32 v85, v73, v73
	v_fmac_f32_e32 v84, v70, v70
	v_fmac_f32_e32 v85, v72, v72
	v_add_f32_e32 v84, v84, v85
	v_add_f32_e32 v1, v1, v84
	s_waitcnt vmcnt(27)
	v_mul_f32_e32 v84, v67, v67
	v_mul_f32_e32 v85, v69, v69
	v_fmac_f32_e32 v84, v66, v66
	v_fmac_f32_e32 v85, v68, v68
	v_add_f32_e32 v84, v84, v85
	v_add_f32_e32 v1, v1, v84
	s_waitcnt vmcnt(24)
	v_mul_f32_e32 v84, v63, v63
	v_mul_f32_e32 v85, v65, v65
	v_fmac_f32_e32 v84, v62, v62
	v_fmac_f32_e32 v85, v64, v64
	v_add_f32_e32 v84, v84, v85
	v_mul_f32_e32 v85, v59, v59
	v_mul_f32_e32 v86, v61, v61
	v_fmac_f32_e32 v85, v58, v58
	v_fmac_f32_e32 v86, v60, v60
	v_add_f32_e32 v85, v85, v86
	v_add_f32_e32 v84, v84, v85
	v_mul_f32_e32 v85, v55, v55
	v_mul_f32_e32 v86, v57, v57
	v_fmac_f32_e32 v85, v54, v54
	v_fmac_f32_e32 v86, v56, v56
	v_add_f32_e32 v85, v85, v86
	v_add_f32_dpp v1, v1, v1 quad_perm:[1,0,3,2] row_mask:0xf bank_mask:0xf bound_ctrl:1
	v_add_f32_e32 v84, v84, v85
	s_waitcnt vmcnt(23)
	v_mul_f32_e32 v85, v51, v51
	v_mul_f32_e32 v86, v53, v53
	v_add_f32_dpp v1, v1, v1 quad_perm:[2,3,0,1] row_mask:0xf bank_mask:0xf bound_ctrl:1
	v_fmac_f32_e32 v85, v50, v50
	v_fmac_f32_e32 v86, v52, v52
	v_add_f32_dpp v1, v1, v1 row_half_mirror row_mask:0xf bank_mask:0xf bound_ctrl:1
	v_add_f32_e32 v85, v85, v86
	v_add_f32_e32 v84, v84, v85
	v_add_f32_dpp v1, v1, v1 row_ror:8 row_mask:0xf bank_mask:0xf bound_ctrl:1
	v_mov_b32_e32 v85, v1
	s_nop 1
	v_permlane16_swap_b32_e32 v1, v85
	v_add_f32_e32 v85, v1, v85
	s_nop 0
	v_add_f32_dpp v1, v84, v84 quad_perm:[1,0,3,2] row_mask:0xf bank_mask:0xf bound_ctrl:1
	v_mov_b32_e32 v87, v85
	s_nop 1
	v_permlane32_swap_b32_e32 v85, v87
	v_add_f32_dpp v1, v1, v1 quad_perm:[2,3,0,1] row_mask:0xf bank_mask:0xf bound_ctrl:1
	s_mov_b32 s4, 0x1400000
	s_nop 0
	v_add_f32_dpp v1, v1, v1 row_half_mirror row_mask:0xf bank_mask:0xf bound_ctrl:1
	s_nop 1
	v_add_f32_dpp v1, v1, v1 row_ror:8 row_mask:0xf bank_mask:0xf bound_ctrl:1
	v_mov_b32_e32 v84, v1
	s_nop 1
	v_permlane16_swap_b32_e32 v1, v84
	v_add_f32_e32 v84, v1, v84
	v_mov_b32_e32 v86, v84
	s_nop 1
	v_permlane32_swap_b32_e32 v84, v86
	v_pk_add_f32 v[84:85], v[84:85], v[86:87]
	s_nop 0
	v_pk_fma_f32 v[84:85], v[84:85], s[16:17], v[134:135] op_sel_hi:[1,0,0]
	s_nop 0
	v_mul_f32_e32 v1, 0x4b800000, v85
	v_cmp_gt_f32_e32 vcc, s2, v85
	s_nop 1
	v_cndmask_b32_e32 v1, v85, v1, vcc
	v_rsq_f32_e32 v1, v1
	v_lshrrev_b32_e32 v85, 16, v90
	v_and_or_b32 v83, v83, s20, v85
	global_store_dwordx2 v[88:89], v[82:83], off offset:1536 sc1
	v_mul_f32_e32 v82, 0x45800000, v1
	v_cndmask_b32_e32 v82, v1, v82, vcc
	v_pk_mul_f32 v[78:79], v[78:79], v[82:83] op_sel_hi:[1,0]
	v_pk_mul_f32 v[80:81], v[80:81], v[82:83] op_sel_hi:[1,0]
	v_pk_mul_f32 v[78:79], v[2:3], v[78:79]
	s_nop 0
	v_bfe_u32 v1, v78, 16, 1
	v_add3_u32 v1, v78, v1, s17
	v_bfe_u32 v78, v79, 16, 1
	v_add3_u32 v83, v79, v78, s17
	v_pk_mul_f32 v[78:79], v[4:5], v[80:81]
	v_lshrrev_b32_e32 v1, 16, v1
	v_bfe_u32 v80, v78, 16, 1
	v_add3_u32 v80, v78, v80, s17
	v_bfe_u32 v78, v79, 16, 1
	v_pk_mul_f32 v[74:75], v[74:75], v[82:83] op_sel_hi:[1,0]
	v_add3_u32 v79, v79, v78, s17
	v_and_or_b32 v78, v83, s20, v1
	v_lshrrev_b32_e32 v1, 16, v80
	v_pk_mul_f32 v[74:75], v[6:7], v[74:75]
	v_and_or_b32 v79, v79, s20, v1
	v_add_co_u32_e32 v80, vcc, s22, v106
	v_bfe_u32 v1, v74, 16, 1
	s_nop 0
	v_addc_co_u32_e32 v81, vcc, 0, v107, vcc
	v_pk_mul_f32 v[76:77], v[76:77], v[82:83] op_sel_hi:[1,0]
	v_add3_u32 v1, v74, v1, s17
	v_bfe_u32 v74, v75, 16, 1
	global_store_dwordx2 v[80:81], v[78:79], off sc1
	v_add3_u32 v78, v75, v74, s17
	v_pk_mul_f32 v[74:75], v[8:9], v[76:77]
	v_pk_mul_f32 v[70:71], v[70:71], v[82:83] op_sel_hi:[1,0]
	v_bfe_u32 v76, v74, 16, 1
	v_add3_u32 v76, v74, v76, s17
	v_bfe_u32 v74, v75, 16, 1
	v_lshrrev_b32_e32 v1, 16, v1
	v_add3_u32 v75, v75, v74, s17
	v_and_or_b32 v74, v78, s20, v1
	v_lshrrev_b32_e32 v1, 16, v76
	v_pk_mul_f32 v[70:71], v[14:15], v[70:71]
	v_and_or_b32 v75, v75, s20, v1
	v_bfe_u32 v1, v70, 16, 1
	v_pk_mul_f32 v[72:73], v[72:73], v[82:83] op_sel_hi:[1,0]
	v_lshl_add_u64 v[76:77], v[106:107], 0, s[14:15]
	v_add3_u32 v1, v70, v1, s17
	v_bfe_u32 v70, v71, 16, 1
	global_store_dwordx2 v[76:77], v[74:75], off offset:512 sc1
	v_add3_u32 v74, v71, v70, s17
	v_pk_mul_f32 v[70:71], v[16:17], v[72:73]
	v_pk_mul_f32 v[66:67], v[66:67], v[82:83] op_sel_hi:[1,0]
	v_bfe_u32 v72, v70, 16, 1
	v_add3_u32 v72, v70, v72, s17
	v_bfe_u32 v70, v71, 16, 1
	v_lshrrev_b32_e32 v1, 16, v1
	v_add3_u32 v71, v71, v70, s17
	v_and_or_b32 v70, v74, s20, v1
	v_lshrrev_b32_e32 v1, 16, v72
	v_pk_mul_f32 v[66:67], v[10:11], v[66:67]
	v_and_or_b32 v71, v71, s20, v1
	v_bfe_u32 v1, v66, 16, 1
	v_pk_mul_f32 v[68:69], v[68:69], v[82:83] op_sel_hi:[1,0]
	v_add3_u32 v1, v66, v1, s17
	v_bfe_u32 v66, v67, 16, 1
	global_store_dwordx2 v[76:77], v[70:71], off offset:1024 sc1
	v_add3_u32 v70, v67, v66, s17
	v_pk_mul_f32 v[66:67], v[12:13], v[68:69]
	v_lshrrev_b32_e32 v1, 16, v1
	v_bfe_u32 v68, v66, 16, 1
	v_add3_u32 v68, v66, v68, s17
	v_bfe_u32 v66, v67, 16, 1
	v_add3_u32 v67, v67, v66, s17
	v_and_or_b32 v66, v70, s20, v1
	v_mul_f32_e32 v1, 0x4b800000, v84
	v_cmp_gt_f32_e32 vcc, s2, v84
	v_lshrrev_b32_e32 v68, 16, v68
	v_and_or_b32 v67, v67, s20, v68
	v_cndmask_b32_e32 v1, v84, v1, vcc
	v_rsq_f32_e32 v1, v1
	global_store_dwordx2 v[76:77], v[66:67], off offset:1536 sc1
	v_mul_f32_e32 v66, 0x45800000, v1
	v_cndmask_b32_e32 v66, v1, v66, vcc
	v_pk_mul_f32 v[62:63], v[62:63], v[66:67] op_sel_hi:[1,0]
	v_pk_mul_f32 v[64:65], v[64:65], v[66:67] op_sel_hi:[1,0]
	v_pk_mul_f32 v[62:63], v[2:3], v[62:63]
	s_nop 0
	v_bfe_u32 v1, v62, 16, 1
	v_add3_u32 v1, v62, v1, s17
	v_bfe_u32 v62, v63, 16, 1
	v_add3_u32 v67, v63, v62, s17
	v_pk_mul_f32 v[62:63], v[4:5], v[64:65]
	v_lshrrev_b32_e32 v1, 16, v1
	v_bfe_u32 v64, v62, 16, 1
	v_add3_u32 v64, v62, v64, s17
	v_bfe_u32 v62, v63, 16, 1
	v_pk_mul_f32 v[58:59], v[58:59], v[66:67] op_sel_hi:[1,0]
	v_add3_u32 v63, v63, v62, s17
	v_and_or_b32 v62, v67, s20, v1
	v_lshrrev_b32_e32 v1, 16, v64
	v_pk_mul_f32 v[58:59], v[6:7], v[58:59]
	v_and_or_b32 v63, v63, s20, v1
	v_add_co_u32_e32 v64, vcc, s4, v106
	v_bfe_u32 v1, v58, 16, 1
	s_nop 0
	v_addc_co_u32_e32 v65, vcc, 0, v107, vcc
	v_pk_mul_f32 v[60:61], v[60:61], v[66:67] op_sel_hi:[1,0]
	v_add3_u32 v1, v58, v1, s17
	v_bfe_u32 v58, v59, 16, 1
	global_store_dwordx2 v[64:65], v[62:63], off sc1
	v_add3_u32 v62, v59, v58, s17
	v_pk_mul_f32 v[58:59], v[8:9], v[60:61]
	v_lshrrev_b32_e32 v1, 16, v1
	v_bfe_u32 v60, v58, 16, 1
	v_add3_u32 v60, v58, v60, s17
	v_bfe_u32 v58, v59, 16, 1
	v_pk_mul_f32 v[54:55], v[54:55], v[66:67] op_sel_hi:[1,0]
	v_add3_u32 v59, v59, v58, s17
	v_and_or_b32 v58, v62, s20, v1
	v_lshrrev_b32_e32 v1, 16, v60
	v_pk_mul_f32 v[54:55], v[14:15], v[54:55]
	v_and_or_b32 v59, v59, s20, v1
	s_mov_b64 s[4:5], 0x1400000
	v_bfe_u32 v1, v54, 16, 1
	v_lshl_add_u64 v[60:61], v[106:107], 0, s[4:5]
	v_pk_mul_f32 v[56:57], v[56:57], v[66:67] op_sel_hi:[1,0]
	v_add3_u32 v1, v54, v1, s17
	v_bfe_u32 v54, v55, 16, 1
	global_store_dwordx2 v[60:61], v[58:59], off offset:512 sc1
	v_add3_u32 v58, v55, v54, s17
	v_pk_mul_f32 v[54:55], v[16:17], v[56:57]
	v_lshrrev_b32_e32 v1, 16, v1
	v_bfe_u32 v56, v54, 16, 1
	v_add3_u32 v56, v54, v56, s17
	v_bfe_u32 v54, v55, 16, 1
	v_pk_mul_f32 v[50:51], v[50:51], v[66:67] op_sel_hi:[1,0]
	v_add3_u32 v55, v55, v54, s17
	v_and_or_b32 v54, v58, s20, v1
	v_lshrrev_b32_e32 v1, 16, v56
	v_pk_mul_f32 v[50:51], v[10:11], v[50:51]
	v_and_or_b32 v55, v55, s20, v1
	v_bfe_u32 v1, v50, 16, 1
	v_pk_mul_f32 v[52:53], v[52:53], v[66:67] op_sel_hi:[1,0]
	v_add3_u32 v1, v50, v1, s17
	v_bfe_u32 v50, v51, 16, 1
	v_pk_mul_f32 v[52:53], v[12:13], v[52:53]
	v_lshrrev_b32_e32 v1, 16, v1
	v_add3_u32 v50, v51, v50, s17
	v_and_or_b32 v50, v50, s20, v1
	v_bfe_u32 v1, v52, 16, 1
	v_bfe_u32 v51, v53, 16, 1
	v_add3_u32 v1, v52, v1, s17
	v_add3_u32 v51, v53, v51, s17
	s_waitcnt vmcnt(27)
	v_mul_f32_e32 v52, v47, v47
	v_mul_f32_e32 v53, v49, v49
	v_fmac_f32_e32 v52, v46, v46
	v_fmac_f32_e32 v53, v48, v48
	global_store_dwordx2 v[60:61], v[54:55], off offset:1024 sc1
	v_add_f32_e32 v52, v52, v53
	v_mul_f32_e32 v53, v43, v43
	v_mul_f32_e32 v54, v45, v45
	v_fmac_f32_e32 v53, v42, v42
	v_fmac_f32_e32 v54, v44, v44
	v_add_f32_e32 v53, v53, v54
	v_add_f32_e32 v52, v52, v53
	v_mul_f32_e32 v53, v39, v39
	v_mul_f32_e32 v54, v41, v41
	v_fmac_f32_e32 v53, v38, v38
	v_fmac_f32_e32 v54, v40, v40
	v_add_f32_e32 v53, v53, v54
	v_add_f32_e32 v52, v52, v53
	s_waitcnt vmcnt(27)
	v_mul_f32_e32 v53, v35, v35
	v_mul_f32_e32 v54, v37, v37
	v_fmac_f32_e32 v53, v34, v34
	v_fmac_f32_e32 v54, v36, v36
	v_add_f32_e32 v53, v53, v54
	v_add_f32_e32 v52, v52, v53
	s_waitcnt vmcnt(24)
	v_mul_f32_e32 v53, v31, v31
	v_mul_f32_e32 v54, v33, v33
	v_fmac_f32_e32 v53, v30, v30
	v_fmac_f32_e32 v54, v32, v32
	v_add_f32_e32 v53, v53, v54
	v_mul_f32_e32 v54, v27, v27
	v_mul_f32_e32 v55, v29, v29
	v_fmac_f32_e32 v54, v26, v26
	v_fmac_f32_e32 v55, v28, v28
	v_add_f32_e32 v54, v54, v55
	v_add_f32_e32 v53, v53, v54
	v_mul_f32_e32 v54, v23, v23
	v_mul_f32_e32 v55, v25, v25
	v_add_f32_dpp v52, v52, v52 quad_perm:[1,0,3,2] row_mask:0xf bank_mask:0xf bound_ctrl:1
	v_fmac_f32_e32 v54, v22, v22
	v_fmac_f32_e32 v55, v24, v24
	v_add_f32_dpp v52, v52, v52 quad_perm:[2,3,0,1] row_mask:0xf bank_mask:0xf bound_ctrl:1
	v_add_f32_e32 v54, v54, v55
	v_add_f32_e32 v54, v53, v54
	v_add_f32_dpp v52, v52, v52 row_half_mirror row_mask:0xf bank_mask:0xf bound_ctrl:1
	s_waitcnt vmcnt(23)
	v_mul_f32_e32 v53, v19, v19
	v_mul_f32_e32 v55, v21, v21
	v_add_f32_dpp v52, v52, v52 row_ror:8 row_mask:0xf bank_mask:0xf bound_ctrl:1
	v_fmac_f32_e32 v53, v18, v18
	v_fmac_f32_e32 v55, v20, v20
	v_add_f32_e32 v55, v53, v55
	v_mov_b32_e32 v53, v52
	s_nop 1
	v_permlane16_swap_b32_e32 v52, v53
	v_add_f32_e32 v53, v52, v53
	v_add_f32_e32 v52, v54, v55
	v_mov_b32_e32 v55, v53
	s_nop 1
	v_permlane32_swap_b32_e32 v53, v55
	v_add_f32_dpp v52, v52, v52 quad_perm:[1,0,3,2] row_mask:0xf bank_mask:0xf bound_ctrl:1
	v_lshrrev_b32_e32 v1, 16, v1
	v_and_or_b32 v51, v51, s20, v1
	v_add_f32_dpp v52, v52, v52 quad_perm:[2,3,0,1] row_mask:0xf bank_mask:0xf bound_ctrl:1
	global_store_dwordx2 v[60:61], v[50:51], off offset:1536 sc1
	v_lshl_add_u64 v[50:51], v[106:107], 0, s[12:13]
	v_add_f32_dpp v52, v52, v52 row_half_mirror row_mask:0xf bank_mask:0xf bound_ctrl:1
	s_mov_b64 s[4:5], 0x1c00000
	s_nop 0
	v_add_f32_dpp v52, v52, v52 row_ror:8 row_mask:0xf bank_mask:0xf bound_ctrl:1
	v_mov_b32_e32 v54, v52
	s_nop 1
	v_permlane16_swap_b32_e32 v52, v54
	v_add_f32_e32 v52, v52, v54
	v_mov_b32_e32 v54, v52
	s_nop 1
	v_permlane32_swap_b32_e32 v52, v54
	v_pk_add_f32 v[52:53], v[52:53], v[54:55]
	s_nop 0
	v_pk_fma_f32 v[52:53], v[52:53], s[16:17], v[134:135] op_sel_hi:[1,0,0]
	s_nop 0
	v_mul_f32_e32 v54, 0x4b800000, v53
	v_cmp_gt_f32_e32 vcc, s2, v53
	s_nop 1
	v_cndmask_b32_e32 v53, v53, v54, vcc
	v_rsq_f32_e32 v53, v53
	s_nop 0
	v_mul_f32_e32 v1, 0x45800000, v53
	v_cndmask_b32_e32 v54, v53, v1, vcc
	v_pk_mul_f32 v[46:47], v[46:47], v[54:55] op_sel_hi:[1,0]
	v_pk_mul_f32 v[48:49], v[48:49], v[54:55] op_sel_hi:[1,0]
	v_pk_mul_f32 v[46:47], v[2:3], v[46:47]
	v_pk_mul_f32 v[48:49], v[4:5], v[48:49]
	v_bfe_u32 v1, v46, 16, 1
	v_add3_u32 v1, v46, v1, s17
	v_bfe_u32 v46, v47, 16, 1
	v_lshrrev_b32_e32 v1, 16, v1
	v_add3_u32 v46, v47, v46, s17
	v_and_or_b32 v46, v46, s20, v1
	v_bfe_u32 v1, v48, 16, 1
	v_add3_u32 v1, v48, v1, s17
	v_bfe_u32 v47, v49, 16, 1
	v_pk_mul_f32 v[42:43], v[42:43], v[54:55] op_sel_hi:[1,0]
	v_lshrrev_b32_e32 v1, 16, v1
	v_add3_u32 v47, v49, v47, s17
	v_pk_mul_f32 v[42:43], v[6:7], v[42:43]
	v_and_or_b32 v47, v47, s20, v1
	v_bfe_u32 v1, v42, 16, 1
	v_pk_mul_f32 v[44:45], v[44:45], v[54:55] op_sel_hi:[1,0]
	v_add3_u32 v1, v42, v1, s17
	v_bfe_u32 v42, v43, 16, 1
	v_pk_mul_f32 v[44:45], v[8:9], v[44:45]
	v_lshrrev_b32_e32 v1, 16, v1
	v_add3_u32 v42, v43, v42, s17
	v_and_or_b32 v42, v42, s20, v1
	v_bfe_u32 v1, v44, 16, 1
	v_add3_u32 v1, v44, v1, s17
	v_bfe_u32 v43, v45, 16, 1
	v_pk_mul_f32 v[38:39], v[38:39], v[54:55] op_sel_hi:[1,0]
	v_lshrrev_b32_e32 v1, 16, v1
	v_add3_u32 v43, v45, v43, s17
	v_pk_mul_f32 v[38:39], v[14:15], v[38:39]
	v_and_or_b32 v43, v43, s20, v1
	v_bfe_u32 v1, v38, 16, 1
	v_pk_mul_f32 v[40:41], v[40:41], v[54:55] op_sel_hi:[1,0]
	v_add3_u32 v1, v38, v1, s17
	v_bfe_u32 v38, v39, 16, 1
	v_pk_mul_f32 v[40:41], v[16:17], v[40:41]
	v_lshrrev_b32_e32 v1, 16, v1
	v_add3_u32 v38, v39, v38, s17
	v_and_or_b32 v38, v38, s20, v1
	v_bfe_u32 v1, v40, 16, 1
	v_add3_u32 v1, v40, v1, s17
	v_bfe_u32 v39, v41, 16, 1
	v_pk_mul_f32 v[34:35], v[34:35], v[54:55] op_sel_hi:[1,0]
	v_lshrrev_b32_e32 v1, 16, v1
	v_add3_u32 v39, v41, v39, s17
	v_pk_mul_f32 v[34:35], v[10:11], v[34:35]
	v_and_or_b32 v39, v39, s20, v1
	v_bfe_u32 v1, v34, 16, 1
	v_pk_mul_f32 v[36:37], v[36:37], v[54:55] op_sel_hi:[1,0]
	v_add3_u32 v1, v34, v1, s17
	v_bfe_u32 v34, v35, 16, 1
	v_add_co_u32_e32 v48, vcc, s21, v106
	v_pk_mul_f32 v[36:37], v[12:13], v[36:37]
	v_lshrrev_b32_e32 v1, 16, v1
	v_add3_u32 v34, v35, v34, s17
	v_addc_co_u32_e32 v49, vcc, 0, v107, vcc
	v_and_or_b32 v34, v34, s20, v1
	v_bfe_u32 v1, v36, 16, 1
	v_add3_u32 v1, v36, v1, s17
	v_mul_f32_e32 v36, 0x4b800000, v52
	v_cmp_gt_f32_e32 vcc, s2, v52
	v_bfe_u32 v35, v37, 16, 1
	v_lshrrev_b32_e32 v1, 16, v1
	v_cndmask_b32_e32 v36, v52, v36, vcc
	v_rsq_f32_e32 v36, v36
	v_add3_u32 v35, v37, v35, s17
	v_and_or_b32 v35, v35, s20, v1
	global_store_dwordx2 v[48:49], v[46:47], off sc1
	v_mul_f32_e32 v1, 0x45800000, v36
	global_store_dwordx2 v[50:51], v[42:43], off offset:512 sc1
	global_store_dwordx2 v[50:51], v[38:39], off offset:1024 sc1
	global_store_dwordx2 v[50:51], v[34:35], off offset:1536 sc1
	v_cndmask_b32_e32 v34, v36, v1, vcc
	v_pk_mul_f32 v[30:31], v[30:31], v[34:35] op_sel_hi:[1,0]
	v_pk_mul_f32 v[32:33], v[32:33], v[34:35] op_sel_hi:[1,0]
	v_pk_mul_f32 v[2:3], v[2:3], v[30:31]
	v_pk_mul_f32 v[4:5], v[4:5], v[32:33]
	v_bfe_u32 v1, v2, 16, 1
	v_add3_u32 v1, v2, v1, s17
	v_bfe_u32 v2, v3, 16, 1
	v_lshrrev_b32_e32 v1, 16, v1
	v_add3_u32 v2, v3, v2, s17
	v_and_or_b32 v2, v2, s20, v1
	v_bfe_u32 v1, v4, 16, 1
	v_lshl_add_u64 v[36:37], v[106:107], 0, s[4:5]
	v_add3_u32 v1, v4, v1, s17
	v_bfe_u32 v3, v5, 16, 1
	s_mov_b32 s4, 0x1c00000
	v_lshrrev_b32_e32 v1, 16, v1
	v_add3_u32 v3, v5, v3, s17
	v_add_co_u32_e32 v4, vcc, s4, v106
	v_and_or_b32 v3, v3, s20, v1
	s_nop 0
	v_addc_co_u32_e32 v5, vcc, 0, v107, vcc
	global_store_dwordx2 v[4:5], v[2:3], off sc1
	v_pk_mul_f32 v[2:3], v[26:27], v[34:35] op_sel_hi:[1,0]
	v_pk_mul_f32 v[4:5], v[28:29], v[34:35] op_sel_hi:[1,0]
	v_pk_mul_f32 v[2:3], v[6:7], v[2:3]
	v_pk_mul_f32 v[4:5], v[8:9], v[4:5]
	v_bfe_u32 v1, v2, 16, 1
	v_add3_u32 v1, v2, v1, s17
	v_bfe_u32 v2, v3, 16, 1
	v_lshrrev_b32_e32 v1, 16, v1
	v_add3_u32 v2, v3, v2, s17
	v_and_or_b32 v2, v2, s20, v1
	v_bfe_u32 v1, v4, 16, 1
	v_add3_u32 v1, v4, v1, s17
	v_bfe_u32 v3, v5, 16, 1
	v_lshrrev_b32_e32 v1, 16, v1
	v_add3_u32 v3, v5, v3, s17
	v_and_or_b32 v3, v3, s20, v1
	global_store_dwordx2 v[36:37], v[2:3], off offset:512 sc1
	v_pk_mul_f32 v[2:3], v[22:23], v[34:35] op_sel_hi:[1,0]
	v_pk_mul_f32 v[4:5], v[24:25], v[34:35] op_sel_hi:[1,0]
	v_pk_mul_f32 v[2:3], v[14:15], v[2:3]
	v_pk_mul_f32 v[4:5], v[16:17], v[4:5]
	v_bfe_u32 v1, v2, 16, 1
	v_add3_u32 v1, v2, v1, s17
	v_bfe_u32 v2, v3, 16, 1
	v_lshrrev_b32_e32 v1, 16, v1
	v_add3_u32 v2, v3, v2, s17
	v_and_or_b32 v2, v2, s20, v1
	v_bfe_u32 v1, v4, 16, 1
	v_add3_u32 v1, v4, v1, s17
	v_bfe_u32 v3, v5, 16, 1
	v_lshrrev_b32_e32 v1, 16, v1
	v_add3_u32 v3, v5, v3, s17
	v_and_or_b32 v3, v3, s20, v1
	global_store_dwordx2 v[36:37], v[2:3], off offset:1024 sc1
	v_pk_mul_f32 v[2:3], v[18:19], v[34:35] op_sel_hi:[1,0]
	v_pk_mul_f32 v[4:5], v[20:21], v[34:35] op_sel_hi:[1,0]
	v_pk_mul_f32 v[2:3], v[10:11], v[2:3]
	v_pk_mul_f32 v[4:5], v[12:13], v[4:5]
	v_bfe_u32 v1, v2, 16, 1
	v_add3_u32 v1, v2, v1, s17
	v_bfe_u32 v2, v3, 16, 1
	v_lshrrev_b32_e32 v1, 16, v1
	v_add3_u32 v2, v3, v2, s17
	v_and_or_b32 v2, v2, s20, v1
	v_bfe_u32 v1, v4, 16, 1
	v_add3_u32 v1, v4, v1, s17
	v_bfe_u32 v3, v5, 16, 1
	v_lshrrev_b32_e32 v1, 16, v1
	v_add3_u32 v3, v5, v3, s17
	v_and_or_b32 v3, v3, s20, v1
	global_store_dwordx2 v[36:37], v[2:3], off offset:1536 sc1
	s_cbranch_scc1 .LBB0_69
	s_lshl_b64 s[4:5], s[62:63], 10
	s_lshl_b64 s[4:5], s[4:5], 2
	s_add_u32 s4, s42, s4
	s_addc_u32 s5, s43, s5
	global_load_dwordx4 v[2:5], v130, s[4:5] nt
	global_load_dwordx4 v[6:9], v130, s[4:5] offset:1024 nt
	global_load_dwordx4 v[10:13], v130, s[4:5] offset:2048 nt
	global_load_dwordx4 v[14:17], v130, s[4:5] offset:3072 nt
	v_lshl_add_u64 v[30:31], s[54:55], 0, v[130:131]
	global_load_dwordx4 v[18:21], v[30:31], off
	global_load_dwordx4 v[22:25], v[30:31], off offset:1024
	global_load_dwordx4 v[26:29], v[30:31], off offset:2048
	v_mov_b32_e32 v1, 0x358637bd
	global_load_dwordx4 v[30:33], v[30:31], off offset:3072
	s_add_u32 s4, s6, s10
	s_addc_u32 s5, s7, s11
	v_lshl_add_u64 v[34:35], s[4:5], 0, v[132:133]
	v_lshl_add_u64 v[36:37], v[34:35], 0, s[8:9]
	v_add_co_u32_e64 v34, s[6:7], s3, v34
	s_waitcnt vmcnt(7)
	v_mul_f32_e32 v38, v3, v3
	v_mul_f32_e32 v39, v5, v5
	s_waitcnt vmcnt(6)
	v_mul_f32_e32 v40, v7, v7
	v_mul_f32_e32 v41, v9, v9
	s_waitcnt vmcnt(5)
	v_mul_f32_e32 v42, v11, v11
	v_mul_f32_e32 v43, v13, v13
	v_fmac_f32_e32 v38, v2, v2
	v_fmac_f32_e32 v39, v4, v4
	v_fmac_f32_e32 v40, v6, v6
	v_fmac_f32_e32 v41, v8, v8
	s_waitcnt vmcnt(4)
	v_mul_f32_e32 v44, v15, v15
	v_mul_f32_e32 v45, v17, v17
	v_fmac_f32_e32 v42, v10, v10
	v_fmac_f32_e32 v43, v12, v12
	v_add_f32_e32 v38, v38, v39
	v_add_f32_e32 v39, v40, v41
	v_fmac_f32_e32 v44, v14, v14
	v_fmac_f32_e32 v45, v16, v16
	v_add_f32_e32 v40, v42, v43
	v_add_f32_e32 v38, v38, v39
	v_add_f32_e32 v41, v44, v45
	v_add_f32_e32 v38, v38, v40
	v_add_f32_e32 v38, v38, v41
	v_addc_co_u32_e64 v35, s[6:7], 0, v35, s[6:7]
	s_nop 0
	v_add_f32_dpp v38, v38, v38 quad_perm:[1,0,3,2] row_mask:0xf bank_mask:0xf bound_ctrl:1
	s_nop 1
	v_add_f32_dpp v38, v38, v38 quad_perm:[2,3,0,1] row_mask:0xf bank_mask:0xf bound_ctrl:1
	s_nop 1
	v_add_f32_dpp v38, v38, v38 row_half_mirror row_mask:0xf bank_mask:0xf bound_ctrl:1
	s_nop 1
	v_add_f32_dpp v38, v38, v38 row_ror:8 row_mask:0xf bank_mask:0xf bound_ctrl:1
	v_mov_b32_e32 v39, v38
	s_nop 1
	v_permlane16_swap_b32_e32 v38, v39
	v_add_f32_e32 v38, v38, v39
	v_mov_b32_e32 v39, v38
	s_nop 1
	v_permlane32_swap_b32_e32 v38, v39
	v_add_f32_e32 v38, v38, v39
	v_fmac_f32_e32 v1, 0x3a800000, v38
	v_mul_f32_e32 v38, 0x4b800000, v1
	v_cmp_gt_f32_e32 vcc, s2, v1
	s_nop 1
	v_cndmask_b32_e32 v1, v1, v38, vcc
	v_rsq_f32_e32 v1, v1
	s_nop 0
	v_mul_f32_e32 v38, 0x45800000, v1
	v_cndmask_b32_e32 v38, v1, v38, vcc
	v_pk_mul_f32 v[2:3], v[2:3], v[38:39] op_sel_hi:[1,0]
	v_pk_mul_f32 v[4:5], v[4:5], v[38:39] op_sel_hi:[1,0]
	v_pk_mul_f32 v[6:7], v[6:7], v[38:39] op_sel_hi:[1,0]
	v_pk_mul_f32 v[8:9], v[8:9], v[38:39] op_sel_hi:[1,0]
	v_pk_mul_f32 v[10:11], v[10:11], v[38:39] op_sel_hi:[1,0]
	v_pk_mul_f32 v[12:13], v[12:13], v[38:39] op_sel_hi:[1,0]
	s_waitcnt vmcnt(3)
	v_pk_mul_f32 v[4:5], v[20:21], v[4:5]
	v_pk_mul_f32 v[2:3], v[18:19], v[2:3]
	s_waitcnt vmcnt(2)
	v_pk_mul_f32 v[8:9], v[24:25], v[8:9]
	v_pk_mul_f32 v[6:7], v[22:23], v[6:7]
	s_waitcnt vmcnt(1)
	v_pk_mul_f32 v[12:13], v[28:29], v[12:13]
	v_pk_mul_f32 v[10:11], v[26:27], v[10:11]
	v_bfe_u32 v1, v2, 16, 1
	v_bfe_u32 v18, v3, 16, 1
	v_bfe_u32 v19, v4, 16, 1
	v_bfe_u32 v20, v5, 16, 1
	v_bfe_u32 v21, v6, 16, 1
	v_bfe_u32 v22, v7, 16, 1
	v_bfe_u32 v23, v8, 16, 1
	v_bfe_u32 v24, v9, 16, 1
	v_bfe_u32 v25, v10, 16, 1
	v_bfe_u32 v26, v11, 16, 1
	v_bfe_u32 v27, v12, 16, 1
	v_add3_u32 v1, v2, v1, s17
	v_add3_u32 v2, v3, v18, s17
	v_add3_u32 v3, v4, v19, s17
	v_add3_u32 v4, v5, v20, s17
	v_add3_u32 v5, v6, v21, s17
	v_add3_u32 v6, v7, v22, s17
	v_add3_u32 v7, v8, v23, s17
	v_bfe_u32 v28, v13, 16, 1
	v_add3_u32 v8, v9, v24, s17
	v_add3_u32 v9, v10, v25, s17
	v_add3_u32 v10, v11, v26, s17
	v_add3_u32 v11, v12, v27, s17
	v_lshrrev_b32_e32 v1, 16, v1
	v_lshrrev_b32_e32 v3, 16, v3
	v_lshrrev_b32_e32 v5, 16, v5
	v_lshrrev_b32_e32 v7, 16, v7
	v_pk_mul_f32 v[14:15], v[14:15], v[38:39] op_sel_hi:[1,0]
	v_add3_u32 v12, v13, v28, s17
	v_lshrrev_b32_e32 v9, 16, v9
	v_lshrrev_b32_e32 v11, 16, v11
	v_and_or_b32 v2, v2, s20, v1
	v_and_or_b32 v3, v4, s20, v3
	v_and_or_b32 v4, v6, s20, v5
	v_and_or_b32 v5, v8, s20, v7
	v_and_or_b32 v6, v10, s20, v9
	v_and_or_b32 v7, v12, s20, v11
	global_store_dwordx2 v[34:35], v[2:3], off sc1
	global_store_dwordx2 v[36:37], v[4:5], off offset:512 sc1
	global_store_dwordx2 v[36:37], v[6:7], off offset:1024 sc1
	s_waitcnt vmcnt(3)
	v_pk_mul_f32 v[4:5], v[30:31], v[14:15]
	v_pk_mul_f32 v[2:3], v[16:17], v[38:39] op_sel_hi:[1,0]
	v_bfe_u32 v1, v4, 16, 1
	v_add3_u32 v1, v4, v1, s17
	v_bfe_u32 v4, v5, 16, 1
	v_pk_mul_f32 v[2:3], v[32:33], v[2:3]
	v_lshrrev_b32_e32 v1, 16, v1
	v_add3_u32 v4, v5, v4, s17
	v_and_or_b32 v4, v4, s20, v1
	v_bfe_u32 v1, v2, 16, 1
	v_add3_u32 v1, v2, v1, s17
	v_bfe_u32 v2, v3, 16, 1
	v_lshrrev_b32_e32 v1, 16, v1
	v_add3_u32 v2, v3, v2, s17
	v_and_or_b32 v5, v2, s20, v1
	global_store_dwordx2 v[36:37], v[4:5], off offset:1536 sc1
